# FFN-up epilogue: packed v_pk_mul_f32 / v_pk_add_f32 split into scalar ops (bit-identical)
# baseline (speedup 1.0000x reference)
; __device__ __forceinline__ float rstd_of(const float* SSQ, size_t row) { const f32x4 s4 = *(const f32x4*)(SSQ + row * 4); return rsqrtf(((s4[0] + s4[1]) + (s4[2] + s4[3])) * (1.0f / 1024.0f) + 1e-6f); }
; #define SSQ WSL(float, WS_SSQ)
; #define EL WSL(float, WS_EL)
;     __device__ __forceinline__ void operator()(const f32x4 (&acc_)[2][2][4][2], const Unit& u, int wr, int wc, int fr_in, int fq_in) const {
;     ...
;         { const int jc0 = u.pn * 128 + wc * 32 + 8 * fq;
; #pragma unroll
;           for (int bj = 0; bj < 2; ++bj) { const float* wp = cw + bj * 2816 + jc0;
;               Wn[bj][0] = *(const f32x4*)(wp); Wn[bj][1] = *(const f32x4*)(wp + 5632); Wn[bj][2] = *(const f32x4*)(wp + 2 * 5632); Wn[bj][3] = *(const f32x4*)(cb + bj * 2816 + jc0); } }
; #pragma unroll
;         for (int ai = 0; ai < 2; ++ai)
; #pragma unroll
;             for (int m = 0; m < 4; ++m) { const float rs0 = rstd_of(SSQ, (size_t)(u.pm * BM + ai * HALF + wr * 64 + m * 16 + fr));
; #pragma unroll
;                 for (int bj = 0; bj < 2; ++bj)
; #pragma unroll
;                     for (int n = 0; n < 2; ++n) acc[ai][bj][m][n] = acc[ai][bj][m][n] * rs0; }
;         const int pcol = u.pn * 256 + wc * 32 + 8 * fq, jcol = u.pn * 128 + wc * 32 + 8 * fq;
;         if (fr >= 14) {
;             const int rr = fr - 14;
; #pragma unroll
;             for (int ai = 0; ai < 2; ++ai)
; #pragma unroll
;                 for (int bj = 0; bj < 2; ++bj)
; #pragma unroll
;                     for (int n = 0; n < 2; ++n) halo[(((((ai * 2 + wr) * 2 + rr) * 4 + wc) * 2 + bj) * 4 + fq) * 2 + n] = acc[ai][bj][3][n];
;             if (wr == 1) { float* e = EL + ((size_t)u.pm * 2 + rr) * 5632 + pcol;
; #pragma unroll
;                 for (int bj = 0; bj < 2; ++bj)
; #pragma unroll
;                     for (int n = 0; n < 2; ++n) *(f32x4*)(e + bj * 128 + n * 4) = acc[1][bj][3][n]; }
.LBB0_1044:
	v_mov_b32_e32 v230, v241
	v_mov_b32_e32 v0, v242
	s_lshl_b32 s4, s9, 7
	s_or_b32 s4, s4, s56
	v_lshlrev_b32_e32 v203, 3, v0
	v_add_u32_e32 v224, s4, v203
	v_ashrrev_i32_e32 v225, 31, v224
	v_lshlrev_b64 v[82:83], 2, v[224:225]
	v_lshl_add_u64 v[196:197], s[14:15], 0, v[82:83]
	v_lshl_add_u64 v[194:195], s[16:17], 0, v[82:83]
	v_add_co_u32_e32 v82, vcc, 0x5000, v196
	global_load_dwordx4 v[102:105], v[196:197], off
	s_nop 0
	v_addc_co_u32_e32 v83, vcc, 0, v197, vcc
	global_load_dwordx4 v[106:109], v[82:83], off offset:2048
	v_add_co_u32_e32 v82, vcc, 0xb000, v196
	s_movk_i32 s5, 0x2000
	s_nop 0
	v_addc_co_u32_e32 v83, vcc, 0, v197, vcc
	v_add_co_u32_e32 v198, vcc, s5, v196
	s_mov_b32 s4, 0x8000
	s_nop 0
	v_addc_co_u32_e32 v199, vcc, 0, v197, vcc
	v_add_co_u32_e32 v86, vcc, s4, v196
	s_lshl_b32 s4, s8, 8
	s_add_i32 s4, s4, s55
	v_add_u32_e32 v228, s4, v230
	v_ashrrev_i32_e32 v229, 31, v228
	v_add_u32_e32 v222, 16, v228
	v_lshl_add_u64 v[154:155], v[228:229], 4, s[26:27]
	v_ashrrev_i32_e32 v223, 31, v222
	v_add_u32_e32 v220, 32, v228
	global_load_dwordx4 v[110:113], v[82:83], off
	s_nop 0
	global_load_dwordx4 v[82:85], v[194:195], off
	global_load_dwordx4 v[178:181], v[154:155], off
	v_lshl_add_u64 v[154:155], v[222:223], 4, s[26:27]
	v_ashrrev_i32_e32 v221, 31, v220
	global_load_dwordx4 v[174:177], v[154:155], off
	v_lshl_add_u64 v[154:155], v[220:221], 4, s[26:27]
	global_load_dwordx4 v[154:157], v[154:155], off
	v_add_u32_e32 v218, 48, v228
	v_ashrrev_i32_e32 v219, 31, v218
	v_addc_co_u32_e32 v87, vcc, 0, v197, vcc
	global_load_dwordx4 v[94:97], v[86:87], off offset:1024
	v_add_co_u32_e32 v86, vcc, 0xd000, v196
	s_mov_b32 s4, 0x358637bd
	s_nop 0
	v_addc_co_u32_e32 v87, vcc, 0, v197, vcc
	global_load_dwordx4 v[98:101], v[86:87], off offset:3072
	v_add_co_u32_e32 v86, vcc, s5, v194
	v_mov_b64_e32 v[226:227], s[4:5]
	s_mov_b32 s6, 0x3a800000
	v_addc_co_u32_e32 v87, vcc, 0, v195, vcc
	s_mov_b32 s4, 0x800000
	v_add_u32_e32 v216, 0x80, v228
	v_ashrrev_i32_e32 v217, 31, v216
	v_add_u32_e32 v212, 0x90, v228
	v_ashrrev_i32_e32 v213, 31, v212
	v_add_u32_e32 v214, 0xa0, v228
	v_ashrrev_i32_e32 v215, 31, v214
	global_load_dwordx4 v[90:93], v[198:199], off offset:3072
	s_mov_b32 s76, 0x3a800000
	global_load_dwordx4 v[86:89], v[86:87], off offset:3072
	s_waitcnt vmcnt(0)
	v_mov_b32_e32 v166, v155
	v_mov_b32_e32 v167, v156
	v_mov_b32_e32 v155, v157
	v_add_f32_e32 v166, v166, v154
	v_add_f32_e32 v167, v167, v155
	v_lshl_add_u64 v[154:155], v[218:219], 4, s[26:27]
	global_load_dwordx4 v[154:157], v[154:155], off
	s_waitcnt vmcnt(0)
	v_mov_b32_e32 v168, v155
	v_mov_b32_e32 v169, v156
	v_mov_b32_e32 v155, v157
	v_add_f32_e32 v154, v168, v154
	v_add_f32_e32 v155, v169, v155
	v_mov_b32_e32 v157, v166
	v_mov_b32_e32 v156, v154
	v_mov_b32_e32 v166, v155
	v_add_f32_e32 v154, v156, v166
	v_add_f32_e32 v155, v157, v167
	s_nop 0
	v_pk_fma_f32 v[232:233], v[154:155], s[6:7], v[226:227] op_sel_hi:[1,0,0]
	s_nop 0
	v_cmp_gt_f32_e32 vcc, s4, v232
	v_mul_f32_e32 v154, 0x4b800000, v232
	v_cmp_gt_f32_e64 s[12:13], s4, v233
	v_cndmask_b32_e32 v154, v232, v154, vcc
	v_rsq_f32_e32 v154, v154
	s_nop 0
	v_mul_f32_e32 v155, 0x45800000, v154
	v_cndmask_b32_e32 v154, v154, v155, vcc
	v_mul_f32_e32 v166, v142, v154
	v_mul_f32_e32 v167, v143, v154
	v_lshl_add_u64 v[142:143], v[216:217], 4, s[26:27]
	v_mul_f32_e32 v172, v152, v154
	v_mul_f32_e32 v173, v153, v154
	v_mul_f32_e32 v170, v150, v154
	v_mul_f32_e32 v171, v151, v154
	v_mul_f32_e32 v56, v56, v154
	v_mul_f32_e32 v57, v57, v154
	v_mul_f32_e32 v54, v54, v154
	v_mul_f32_e32 v55, v55, v154
	v_mul_f32_e32 v168, v144, v154
	v_mul_f32_e32 v169, v145, v154
	v_mul_f32_e32 v52, v52, v154
	v_mul_f32_e32 v53, v53, v154
	v_mul_f32_e32 v50, v50, v154
	v_mul_f32_e32 v51, v51, v154
	global_load_dwordx4 v[154:157], v[142:143], off
	v_lshl_add_u64 v[142:143], v[212:213], 4, s[26:27]
	global_load_dwordx4 v[150:153], v[142:143], off
	v_lshl_add_u64 v[142:143], v[214:215], 4, s[26:27]
	global_load_dwordx4 v[142:145], v[142:143], off
	s_waitcnt vmcnt(0)
	v_mov_b32_e32 v200, v143
	v_mov_b32_e32 v201, v144
	v_mov_b32_e32 v143, v145
	v_add_f32_e32 v142, v200, v142
	v_add_f32_e32 v143, v201, v143
	v_add_u32_e32 v200, 0xb0, v228
	v_ashrrev_i32_e32 v201, 31, v200
	v_lshl_add_u64 v[144:145], v[200:201], 4, s[26:27]
	global_load_dwordx4 v[204:207], v[144:145], off
	v_lshlrev_b32_e32 v201, 5, v0
	v_cndmask_b32_e64 v0, 0, 1, s[18:19]
	s_waitcnt vmcnt(0)
	v_mov_b32_e32 v144, v205
	v_mov_b32_e32 v145, v206
	v_mov_b32_e32 v205, v207
	v_add_f32_e32 v144, v144, v204
	v_add_f32_e32 v145, v145, v205
	v_mov_b32_e32 v205, v142
	v_mov_b32_e32 v204, v144
	v_mov_b32_e32 v142, v145
	v_add_f32_e32 v142, v204, v142
	v_add_f32_e32 v143, v205, v143
	s_nop 0
	v_pk_fma_f32 v[226:227], v[142:143], s[6:7], v[226:227] op_sel_hi:[1,0,0]
	s_nop 0
	v_cmp_gt_f32_e32 vcc, s4, v226
	v_mul_f32_e32 v142, 0x4b800000, v226
	v_cmp_gt_f32_e64 s[10:11], s4, v227
	v_cndmask_b32_e32 v142, v226, v142, vcc
	v_rsq_f32_e32 v142, v142
	s_lshl_b32 s4, s9, 8
	s_or_b32 s4, s4, s56
	v_add_u32_e32 v236, s4, v203
	v_mul_f32_e32 v143, 0x45800000, v142
	v_cndmask_b32_e32 v202, v142, v143, vcc
	v_mul_f32_e32 v144, v140, v202
	v_mul_f32_e32 v145, v141, v202
	v_mul_f32_e32 v142, v138, v202
	v_mul_f32_e32 v143, v139, v202
	v_mul_f32_e32 v48, v48, v202
	v_mul_f32_e32 v49, v49, v202
	v_mul_f32_e32 v46, v46, v202
	v_mul_f32_e32 v47, v47, v202
	v_mul_f32_e32 v140, v120, v202
	v_mul_f32_e32 v141, v121, v202
	v_mul_f32_e32 v138, v118, v202
	v_mul_f32_e32 v139, v119, v202
	v_mul_f32_e32 v44, v44, v202
	v_mul_f32_e32 v45, v45, v202
	v_mul_f32_e32 v42, v42, v202
	v_mul_f32_e32 v43, v43, v202
	v_cmp_lt_i32_e32 vcc, 13, v230
	v_cmp_ne_u32_e64 s[4:5], 1, v0
	s_and_saveexec_b64 s[6:7], vcc
	s_cbranch_execz .LBB0_1047
	v_add_u32_e32 v0, -14, v230
	v_lshl_add_u32 v118, v0, 3, s60
	v_or_b32_e32 v119, s59, v118
	v_lshlrev_b32_e32 v119, 7, v119
	v_add_lshl_u32 v118, s61, v118, 7
	v_add3_u32 v119, s66, v119, v201
	v_add3_u32 v118, s66, v118, v201
	s_and_b64 vcc, exec, s[4:5]
	ds_write_b128 v119, v[170:173]
	ds_write_b128 v119, v[54:57] offset:16
	ds_write_b128 v119, v[166:169] offset:128
	ds_write_b128 v119, v[50:53] offset:144
	ds_write_b128 v118, v[142:145]
	ds_write_b128 v118, v[46:49] offset:16
	ds_write_b128 v118, v[138:141] offset:128
	ds_write_b128 v118, v[42:45] offset:144
	s_cbranch_vccnz .LBB0_1047
	s_ashr_i32 s9, s8, 31
	v_lshl_add_u64 v[118:119], s[8:9], 1, v[0:1]
	v_mov_b64_e32 v[120:121], s[24:25]
	s_movk_i32 s9, 0x5800
	v_mad_u64_u32 v[120:121], s[40:41], v118, s9, v[120:121]
	v_mad_i32_i24 v121, v119, s9, v121
	v_ashrrev_i32_e32 v237, 31, v236
	v_lshl_add_u64 v[118:119], v[236:237], 2, v[120:121]
	global_store_dwordx4 v[118:119], v[142:145], off
	global_store_dwordx4 v[118:119], v[46:49], off offset:16
	global_store_dwordx4 v[118:119], v[138:141], off offset:512
	global_store_dwordx4 v[118:119], v[42:45], off offset:528
; __device__ __forceinline__ float rstd_of(const float* SSQ, size_t row) { const f32x4 s4 = *(const f32x4*)(SSQ + row * 4); return rsqrtf(((s4[0] + s4[1]) + (s4[2] + s4[3])) * (1.0f / 1024.0f) + 1e-6f); }
; #define SSQ WSL(float, WS_SSQ)
; #define EF WSL(float, WS_EF)
;     __device__ __forceinline__ void operator()(const f32x4 (&acc_)[2][2][4][2], const Unit& u, int wr, int wc, int fr_in, int fq_in) const {
;     ...
;         for (int ai = 0; ai < 2; ++ai)
; #pragma unroll
;             for (int m = 0; m < 4; ++m) { const float rs0 = rstd_of(SSQ, (size_t)(u.pm * BM + ai * HALF + wr * 64 + m * 16 + fr));
; #pragma unroll
;                 for (int bj = 0; bj < 2; ++bj)
; #pragma unroll
;                     for (int n = 0; n < 2; ++n) acc[ai][bj][m][n] = acc[ai][bj][m][n] * rs0; }
;     ...
;         if (wr == 0 && fr < 2) { float* e = EF + ((size_t)u.pm * 2 + fr) * 5632 + pcol;
; #pragma unroll
;             for (int bj = 0; bj < 2; ++bj)
; #pragma unroll
;                 for (int n = 0; n < 2; ++n) *(f32x4*)(e + bj * 128 + n * 4) = acc[0][bj][0][n]; }
.LBB0_1047:
	s_or_b64 exec, exec, s[6:7]
	v_mov_b32_e32 v118, v179
	v_mov_b32_e32 v119, v180
	v_mov_b32_e32 v179, v181
	v_mov_b32_e32 v120, v175
	v_mov_b32_e32 v121, v176
	v_mov_b32_e32 v175, v177
	v_add_f32_e32 v118, v118, v178
	v_add_f32_e32 v119, v119, v179
	v_add_f32_e32 v120, v120, v174
	v_add_f32_e32 v121, v121, v175
	v_mov_b32_e32 v175, v118
	v_mov_b32_e32 v174, v120
	v_mov_b32_e32 v118, v121
	v_add_f32_e32 v118, v174, v118
	v_add_f32_e32 v119, v175, v119
	v_mov_b32_e32 v0, 0x358637bd
	v_pk_fma_f32 v[234:235], v[118:119], s[76:77], v[0:1] op_sel_hi:[1,0,0]
	s_mov_b32 s9, 0x800000
	v_mul_f32_e32 v0, 0x4b800000, v235
	v_cmp_gt_f32_e64 s[6:7], s9, v235
	v_cmp_gt_f32_e32 vcc, s9, v234
	s_nop 0
	v_cndmask_b32_e64 v0, v235, v0, s[6:7]
	v_rsq_f32_e32 v0, v0
	s_nop 0
	v_mul_f32_e32 v118, 0x45800000, v0
	v_cndmask_b32_e64 v0, v0, v118, s[6:7]
	v_cmp_gt_i32_e64 s[6:7], 2, v230
	v_mul_f32_e32 v164, v164, v0
	v_mul_f32_e32 v165, v165, v0
	v_mul_f32_e32 v162, v162, v0
	v_mul_f32_e32 v163, v163, v0
	v_mul_f32_e32 v120, v160, v0
	v_mul_f32_e32 v121, v161, v0
	v_mul_f32_e32 v118, v158, v0
	v_mul_f32_e32 v119, v159, v0
	v_mul_f32_e32 v148, v148, v0
	v_mul_f32_e32 v149, v149, v0
	v_mul_f32_e32 v146, v146, v0
	v_mul_f32_e32 v147, v147, v0
	v_mul_f32_e32 v116, v116, v0
	v_mul_f32_e32 v117, v117, v0
	v_mul_f32_e32 v114, v114, v0
	v_mul_f32_e32 v115, v115, v0
	s_and_b64 s[42:43], s[28:29], s[6:7]
	s_and_saveexec_b64 s[40:41], s[42:43]
	s_cbranch_execz .LBB0_1049
	s_ashr_i32 s9, s8, 31
	v_ashrrev_i32_e32 v231, 31, v230
	v_lshl_add_u64 v[158:159], s[8:9], 1, v[230:231]
	v_mov_b64_e32 v[160:161], s[22:23]
	s_movk_i32 s31, 0x5800
	v_mad_u64_u32 v[160:161], s[8:9], v158, s31, v[160:161]
	v_mad_i32_i24 v161, v159, s31, v161
	v_ashrrev_i32_e32 v237, 31, v236
	v_lshl_add_u64 v[158:159], v[236:237], 2, v[160:161]
	global_store_dwordx4 v[158:159], v[162:165], off
	global_store_dwordx4 v[158:159], v[118:121], off offset:16
	global_store_dwordx4 v[158:159], v[146:149], off offset:512
	global_store_dwordx4 v[158:159], v[114:117], off offset:528

;     __device__ __forceinline__ void operator()(const f32x4 (&acc_)[2][2][4][2], const Unit& u, int wr, int wc, int fr_in, int fq_in) const {
;     ...
;             for (int m = 0; m < 4; ++m) { const float rs0 = rstd_of(SSQ, (size_t)(u.pm * BM + ai * HALF + wr * 64 + m * 16 + fr));
; #pragma unroll
;                 for (int bj = 0; bj < 2; ++bj)
; #pragma unroll
;                     for (int n = 0; n < 2; ++n) acc[ai][bj][m][n] = acc[ai][bj][m][n] * rs0; }
;     ...
;         for (int n = 0; n < 2; ++n) {
;             f32x4 W0[2], W1[2], W2[2], Bb[2], W0m[2], W1m[2];
; #pragma unroll
;             for (int bj = 0; bj < 2; ++bj) { const float* wp = cw + bj * 2816 + jcol + 4 * n;
;                 if (n == 0) { W0[bj] = Wn[bj][0]; W1[bj] = Wn[bj][1]; W2[bj] = Wn[bj][2]; Bb[bj] = Wn[bj][3]; }
;                 else { W0[bj] = *(const f32x4*)(wp); W1[bj] = *(const f32x4*)(wp + 5632); W2[bj] = *(const f32x4*)(wp + 2 * 5632); Bb[bj] = *(const f32x4*)(cb + bj * 2816 + jcol + 4 * n); }
;                 W1m[bj] = fr == 0 ? W1[bj] : (f32x4){0.f, 0.f, 0.f, 0.f}; W0m[bj] = fr < 2 ? W0[bj] : (f32x4){0.f, 0.f, 0.f, 0.f}; }
; #pragma unroll
;             for (int ai = 0; ai < 2; ++ai)
; #pragma unroll
;                 for (int m = 0; m < 4; ++m) {
;                     f32x4 c[2];
; #pragma unroll
;                     for (int bj = 0; bj < 2; ++bj) {
;                         const f32x4 a = acc[ai][bj][m][n];
;                         f32x4 t1, t2;
;                         if (m > 0) { t1 = (f32x4){0.f, 0.f, 0.f, 0.f}; t2 = t1;
;                         } else {
;                             t1 = (f32x4){0.f, 0.f, 0.f, 0.f}; t2 = t1;
;                             const int sa = (wr == 1) ? ai : 0, sw = (wr == 1) ? 0 : 1;
;                             if ((wr == 1 || ai == 1) && fr < 2) {
;                                 const f32x4 h0 = halo[(((((sa * 2 + sw) * 2 + 0) * 4 + wc) * 2 + bj) * 4 + fq) * 2 + n], h1 = halo[(((((sa * 2 + sw) * 2 + 1) * 4 + wc) * 2 + bj) * 4 + fq) * 2 + n];
;                                 t1 = (fr == 0) ? h1 : (f32x4){0.f, 0.f, 0.f, 0.f}; t2 = (fr == 0) ? h0 : h1;
;                             }
;                         }
; #pragma unroll
;                         for (int i = 0; i < 4; ++i) {
;                             const float ax = a[i];
;                             float v = __builtin_fmaf(W2[bj][i], ax, Bb[bj][i]);
.LBB0_1057:
	s_or_b64 exec, exec, s[42:43]
	v_fmac_f32_e32 v211, v217, v106
	s_waitcnt lgkmcnt(0)
	v_fmac_f32_e32 v211, v174, v102
	v_mul_f32_e32 v174, 0x4b800000, v234
	v_cndmask_b32_e32 v174, v234, v174, vcc
	v_rsq_f32_e32 v174, v174
	v_fmac_f32_e32 v209, v213, v108
	v_fmac_f32_e32 v208, v215, v107
	v_fmac_f32_e32 v209, v176, v104
	v_mul_f32_e32 v176, 0x45800000, v174
	v_fmac_f32_e32 v208, v175, v103
	v_cndmask_b32_e64 v175, 0, v97, s[8:9]
	v_cndmask_b32_e32 v174, v174, v176, vcc
	v_mul_f32_e32 v180, v136, v174
	v_mul_f32_e32 v181, v137, v174
	v_mul_f32_e32 v136, 0x4b800000, v233
	v_cndmask_b32_e64 v136, v233, v136, s[12:13]
	v_rsq_f32_e32 v136, v136
	v_mul_f32_e32 v178, v126, v174
	v_mul_f32_e32 v179, v127, v174
	v_fmac_f32_e32 v204, v203, v109
	v_mul_f32_e32 v230, v134, v174
	v_mul_f32_e32 v231, v135, v174
	v_mul_f32_e32 v126, 0x45800000, v136
	v_cndmask_b32_e64 v134, v136, v126, s[12:13]
	v_fmac_f32_e32 v204, v177, v105
	v_mul_f32_e32 v176, v128, v174
	v_mul_f32_e32 v177, v129, v174
	v_mul_f32_e32 v128, v132, v134
	v_mul_f32_e32 v129, v133, v134
	v_mul_f32_e32 v130, v130, v134
	v_mul_f32_e32 v131, v131, v134
	v_mul_f32_e32 v124, v124, v134
	v_mul_f32_e32 v125, v125, v134
	v_mul_f32_e32 v122, v122, v134
	v_mul_f32_e32 v123, v123, v134
	v_mul_f32_e32 v135, 0xbfb8aa3b, v211
	v_exp_f32_e32 v135, v135
	v_fma_f32 v126, v98, v146, v86
	v_mul_f32_e32 v136, 0xbfb8aa3b, v208
	v_fmac_f32_dpp v126, v146, v94 row_shr:1 row_mask:0xf bank_mask:0xf bound_ctrl:1
	v_add_f32_e32 v135, 1.0, v135
	v_rcp_f32_e32 v135, v135
	v_exp_f32_e32 v136, v136
	v_fmac_f32_dpp v126, v146, v90 row_shr:2 row_mask:0xf bank_mask:0xf bound_ctrl:1
	v_mul_f32_e32 v137, 0xbfb8aa3b, v204
	v_fmac_f32_e32 v126, v210, v94
	v_fmac_f32_e32 v126, v158, v90
	v_mul_f32_e32 v135, v211, v135
	v_mul_f32_e32 v126, v135, v126
	v_add_f32_e32 v135, 1.0, v136
	v_mul_f32_e32 v136, 0xbfb8aa3b, v209
	v_exp_f32_e32 v136, v136
	v_exp_f32_e32 v137, v137
	v_fma_f32 v127, v99, v147, v87
	v_rcp_f32_e32 v135, v135
	v_add_f32_e32 v136, 1.0, v136
	v_fmac_f32_dpp v127, v147, v95 row_shr:1 row_mask:0xf bank_mask:0xf bound_ctrl:1
	v_fma_f32 v132, v100, v148, v88
	v_rcp_f32_e32 v136, v136
	v_add_f32_e32 v137, 1.0, v137
	v_fmac_f32_dpp v127, v147, v91 row_shr:2 row_mask:0xf bank_mask:0xf bound_ctrl:1
	v_fmac_f32_dpp v132, v148, v96 row_shr:1 row_mask:0xf bank_mask:0xf bound_ctrl:1
	v_fma_f32 v133, v101, v149, v89
	v_rcp_f32_e32 v137, v137
	v_fmac_f32_e32 v127, v207, v95
	v_fmac_f32_dpp v132, v148, v92 row_shr:2 row_mask:0xf bank_mask:0xf bound_ctrl:1
	v_fmac_f32_dpp v133, v149, v97 row_shr:1 row_mask:0xf bank_mask:0xf bound_ctrl:1
	v_fmac_f32_e32 v127, v159, v91
	v_fmac_f32_e32 v132, v206, v96
	v_fmac_f32_dpp v133, v149, v93 row_shr:2 row_mask:0xf bank_mask:0xf bound_ctrl:1
	v_mul_f32_e32 v135, v208, v135
	v_fmac_f32_e32 v132, v160, v92
	v_fmac_f32_e32 v133, v205, v97
	v_mul_f32_e32 v127, v135, v127
	v_mul_f32_e32 v135, v209, v136
	v_fmac_f32_e32 v133, v161, v93
	v_mul_f32_e32 v132, v135, v132
	v_mul_f32_e32 v135, v204, v137
	v_fma_f32 v161, v98, v178, v86
	v_mul_f32_e32 v133, v135, v133
	v_fma_f32 v135, v110, v230, v82
	v_fmac_f32_dpp v161, v178, v94 row_shr:1 row_mask:0xf bank_mask:0xf bound_ctrl:1
	v_fmac_f32_dpp v135, v230, v106 row_shr:1 row_mask:0xf bank_mask:0xf bound_ctrl:1
	v_cndmask_b32_e64 v226, 0, v94, s[8:9]
	v_fmac_f32_dpp v161, v178, v90 row_shr:2 row_mask:0xf bank_mask:0xf bound_ctrl:1
	v_fmac_f32_dpp v135, v230, v102 row_shr:2 row_mask:0xf bank_mask:0xf bound_ctrl:1
	v_cndmask_b32_e64 v246, 0, v106, s[8:9]
	v_fmac_f32_dpp v161, v146, v226 row_ror:1 row_mask:0xf bank_mask:0xf
	v_cndmask_b32_e64 v232, 0, v90, s[6:7]
	v_cvt_pk_bf16_f32 v136, v126, v127
	v_mov_b64_e32 v[126:127], s[20:21]
	s_movk_i32 s31, 0x1600
	v_fmac_f32_dpp v135, v162, v246 row_ror:1 row_mask:0xf bank_mask:0xf
	v_fmac_f32_dpp v161, v146, v232 row_ror:2 row_mask:0xf bank_mask:0xf
	v_fma_f32 v146, v99, v179, v87
	v_cndmask_b32_e64 v203, 0, v102, s[6:7]
	v_cvt_pk_bf16_f32 v137, v132, v133
	v_mad_i64_i32 v[132:133], s[12:13], v228, s31, v[126:127]
	v_lshlrev_b64 v[158:159], 1, v[224:225]
	v_fmac_f32_dpp v135, v162, v203 row_ror:2 row_mask:0xf bank_mask:0xf
	v_fmac_f32_dpp v146, v179, v95 row_shr:1 row_mask:0xf bank_mask:0xf bound_ctrl:1
	v_lshl_add_u64 v[132:133], v[132:133], 0, v[158:159]
	v_mul_f32_e32 v162, 0xbfb8aa3b, v135
	v_fmac_f32_dpp v146, v179, v91 row_shr:2 row_mask:0xf bank_mask:0xf bound_ctrl:1
	v_exp_f32_e32 v162, v162
	v_cndmask_b32_e64 v219, 0, v95, s[8:9]
	global_store_dwordx2 v[132:133], v[136:137], off
	v_fma_f32 v136, v111, v231, v83
	v_fmac_f32_dpp v146, v147, v219 row_ror:1 row_mask:0xf bank_mask:0xf
	v_cndmask_b32_e64 v221, 0, v91, s[6:7]
	v_fmac_f32_dpp v136, v231, v107 row_shr:1 row_mask:0xf bank_mask:0xf bound_ctrl:1
	v_fmac_f32_dpp v146, v147, v221 row_ror:2 row_mask:0xf bank_mask:0xf
	v_fma_f32 v147, v100, v176, v88
	v_fmac_f32_dpp v136, v231, v103 row_shr:2 row_mask:0xf bank_mask:0xf bound_ctrl:1
	v_fmac_f32_dpp v147, v176, v96 row_shr:1 row_mask:0xf bank_mask:0xf bound_ctrl:1
	v_cndmask_b32_e64 v237, 0, v107, s[8:9]
	v_fmac_f32_dpp v136, v163, v237 row_ror:1 row_mask:0xf bank_mask:0xf
	v_fmac_f32_dpp v147, v176, v92 row_shr:2 row_mask:0xf bank_mask:0xf bound_ctrl:1
	v_add_f32_e32 v162, 1.0, v162
	v_cndmask_b32_e64 v245, 0, v103, s[6:7]
	v_cndmask_b32_e64 v215, 0, v96, s[8:9]
	v_fmac_f32_dpp v136, v163, v245 row_ror:2 row_mask:0xf bank_mask:0xf
	v_fmac_f32_dpp v147, v148, v215 row_ror:1 row_mask:0xf bank_mask:0xf
	v_rcp_f32_e32 v162, v162
	v_mul_f32_e32 v163, 0xbfb8aa3b, v136
	v_cndmask_b32_e64 v217, 0, v92, s[6:7]
	v_fma_f32 v137, v112, v180, v84
	v_fma_f32 v160, v113, v181, v85
;     __device__ __forceinline__ void operator()(const f32x4 (&acc_)[2][2][4][2], const Unit& u, int wr, int wc, int fr_in, int fq_in) const {
;     ...
;                 for (int m = 0; m < 4; ++m) {
;                     f32x4 c[2];
; #pragma unroll
;                     for (int bj = 0; bj < 2; ++bj) {
;                         const f32x4 a = acc[ai][bj][m][n];
;                         f32x4 t1, t2;
;                         if (m > 0) { t1 = (f32x4){0.f, 0.f, 0.f, 0.f}; t2 = t1;
;                         } else {
;                             t1 = (f32x4){0.f, 0.f, 0.f, 0.f}; t2 = t1;
;                             const int sa = (wr == 1) ? ai : 0, sw = (wr == 1) ? 0 : 1;
;                             if ((wr == 1 || ai == 1) && fr < 2) {
;                                 const f32x4 h0 = halo[(((((sa * 2 + sw) * 2 + 0) * 4 + wc) * 2 + bj) * 4 + fq) * 2 + n], h1 = halo[(((((sa * 2 + sw) * 2 + 1) * 4 + wc) * 2 + bj) * 4 + fq) * 2 + n];
;                                 t1 = (fr == 0) ? h1 : (f32x4){0.f, 0.f, 0.f, 0.f}; t2 = (fr == 0) ? h0 : h1;
;                             }
;                         }
; #pragma unroll
;                         for (int i = 0; i < 4; ++i) {
;                             const float ax = a[i];
;                             float v = __builtin_fmaf(W2[bj][i], ax, Bb[bj][i]);
;                             PG8_FMAC_DPP(v, ax, W1[bj][i], "row_shr:1 row_mask:0xf bank_mask:0xf bound_ctrl:1");
;                             PG8_FMAC_DPP(v, ax, W0[bj][i], "row_shr:2 row_mask:0xf bank_mask:0xf bound_ctrl:1");
;                             if (m > 0) { const float apx = acc[ai][bj][m - 1][n][i];
;                                 PG8_FMAC_DPP(v, apx, W1m[bj][i], "row_ror:1 row_mask:0xf bank_mask:0xf");
;                                 PG8_FMAC_DPP(v, apx, W0m[bj][i], "row_ror:2 row_mask:0xf bank_mask:0xf");
;                             } else { v = __builtin_fmaf(t1[i], W1[bj][i], v); v = __builtin_fmaf(t2[i], W0[bj][i], v); }
;                             c[bj][i] = v;
;                         }
;                     }
;                     float hm[4];
; #pragma unroll
;                     for (int i = 0; i < 4; ++i) { const float g = c[0][i]; hm[i] = g * __builtin_amdgcn_rcpf(1.f + __builtin_amdgcn_exp2f(-1.4426950408889634f * g)) * c[1][i]; }
	v_fmac_f32_dpp v147, v148, v217 row_ror:2 row_mask:0xf bank_mask:0xf
	v_fma_f32 v148, v101, v177, v89
	v_exp_f32_e32 v163, v163
	v_fmac_f32_dpp v137, v180, v108 row_shr:1 row_mask:0xf bank_mask:0xf bound_ctrl:1
	v_fmac_f32_dpp v160, v181, v109 row_shr:1 row_mask:0xf bank_mask:0xf bound_ctrl:1
	v_fmac_f32_dpp v148, v177, v97 row_shr:1 row_mask:0xf bank_mask:0xf bound_ctrl:1
	v_cndmask_b32_e64 v223, 0, v109, s[8:9]
	v_fmac_f32_dpp v137, v180, v104 row_shr:2 row_mask:0xf bank_mask:0xf bound_ctrl:1
	v_fmac_f32_dpp v160, v181, v105 row_shr:2 row_mask:0xf bank_mask:0xf bound_ctrl:1
	v_fmac_f32_dpp v148, v177, v93 row_shr:2 row_mask:0xf bank_mask:0xf bound_ctrl:1
	v_cndmask_b32_e64 v235, 0, v108, s[8:9]
	v_fmac_f32_dpp v137, v164, v235 row_ror:1 row_mask:0xf bank_mask:0xf
	v_fmac_f32_dpp v160, v165, v223 row_ror:1 row_mask:0xf bank_mask:0xf
	v_fmac_f32_dpp v148, v149, v175 row_ror:1 row_mask:0xf bank_mask:0xf
	v_mul_f32_e32 v135, v135, v162
	v_cndmask_b32_e64 v229, 0, v105, s[6:7]
	v_cndmask_b32_e64 v236, 0, v104, s[6:7]
	v_cndmask_b32_e64 v213, 0, v93, s[6:7]
	v_fmac_f32_dpp v137, v164, v236 row_ror:2 row_mask:0xf bank_mask:0xf
	v_fmac_f32_dpp v160, v165, v229 row_ror:2 row_mask:0xf bank_mask:0xf
	v_fmac_f32_dpp v148, v149, v213 row_ror:2 row_mask:0xf bank_mask:0xf
	v_mul_f32_e32 v135, v135, v161
	v_add_f32_e32 v149, 1.0, v163
	v_mul_f32_e32 v161, 0xbfb8aa3b, v137
	v_mul_f32_e32 v162, 0xbfb8aa3b, v160
	v_rcp_f32_e32 v149, v149
	v_exp_f32_e32 v161, v161
	v_exp_f32_e32 v162, v162
	v_mul_f32_e32 v136, v136, v149
	v_add_f32_e32 v149, 1.0, v161
	v_add_f32_e32 v161, 1.0, v162
	v_rcp_f32_e32 v149, v149
	v_rcp_f32_e32 v161, v161
	v_mul_f32_e32 v136, v136, v146
	v_fma_f32 v162, v101, v125, v89
	v_mul_f32_e32 v137, v137, v149
	v_mul_f32_e32 v146, v160, v161
	v_mul_f32_e32 v137, v137, v147
	v_mul_f32_e32 v147, v146, v148
	v_cvt_pk_bf16_f32 v146, v135, v136
	v_fma_f32 v135, v110, v130, v82
	v_fmac_f32_dpp v135, v130, v106 row_shr:1 row_mask:0xf bank_mask:0xf bound_ctrl:1
	v_cvt_pk_bf16_f32 v147, v137, v147
	v_mad_i64_i32 v[136:137], s[12:13], v222, s31, v[126:127]
	v_fmac_f32_dpp v135, v130, v102 row_shr:2 row_mask:0xf bank_mask:0xf bound_ctrl:1
	v_lshl_add_u64 v[136:137], v[136:137], 0, v[158:159]
	v_fmac_f32_dpp v135, v230, v246 row_ror:1 row_mask:0xf bank_mask:0xf
	global_store_dwordx2 v[136:137], v[146:147], off
	v_fmac_f32_dpp v135, v230, v203 row_ror:2 row_mask:0xf bank_mask:0xf
	v_fma_f32 v146, v111, v131, v83
	v_mul_f32_e32 v163, 0xbfb8aa3b, v135
	v_exp_f32_e32 v163, v163
	v_fmac_f32_dpp v146, v131, v107 row_shr:1 row_mask:0xf bank_mask:0xf bound_ctrl:1
	v_fma_f32 v149, v98, v122, v86
	v_fmac_f32_dpp v146, v131, v103 row_shr:2 row_mask:0xf bank_mask:0xf bound_ctrl:1
	v_add_f32_e32 v163, 1.0, v163
	v_fmac_f32_dpp v146, v231, v237 row_ror:1 row_mask:0xf bank_mask:0xf
	v_rcp_f32_e32 v163, v163
	v_fmac_f32_dpp v146, v231, v245 row_ror:2 row_mask:0xf bank_mask:0xf
	v_fma_f32 v147, v112, v128, v84
	v_mul_f32_e32 v164, 0xbfb8aa3b, v146
	v_fma_f32 v148, v113, v129, v85
	v_fmac_f32_dpp v149, v122, v94 row_shr:1 row_mask:0xf bank_mask:0xf bound_ctrl:1
	v_exp_f32_e32 v164, v164
	v_fmac_f32_dpp v147, v128, v108 row_shr:1 row_mask:0xf bank_mask:0xf bound_ctrl:1
	v_fmac_f32_dpp v148, v129, v109 row_shr:1 row_mask:0xf bank_mask:0xf bound_ctrl:1
	v_fmac_f32_dpp v149, v122, v90 row_shr:2 row_mask:0xf bank_mask:0xf bound_ctrl:1
	v_mul_f32_e32 v135, v135, v163
	v_fmac_f32_dpp v147, v128, v104 row_shr:2 row_mask:0xf bank_mask:0xf bound_ctrl:1
	v_fmac_f32_dpp v148, v129, v105 row_shr:2 row_mask:0xf bank_mask:0xf bound_ctrl:1
	v_fmac_f32_dpp v149, v178, v226 row_ror:1 row_mask:0xf bank_mask:0xf
	v_fma_f32 v160, v99, v123, v87
	v_fmac_f32_dpp v147, v180, v235 row_ror:1 row_mask:0xf bank_mask:0xf
	v_fmac_f32_dpp v148, v181, v223 row_ror:1 row_mask:0xf bank_mask:0xf
	v_fmac_f32_dpp v149, v178, v232 row_ror:2 row_mask:0xf bank_mask:0xf
	v_fmac_f32_dpp v160, v123, v95 row_shr:1 row_mask:0xf bank_mask:0xf bound_ctrl:1
	v_fmac_f32_dpp v162, v125, v97 row_shr:1 row_mask:0xf bank_mask:0xf bound_ctrl:1
	v_fma_f32 v161, v100, v124, v88
	v_fmac_f32_dpp v147, v180, v236 row_ror:2 row_mask:0xf bank_mask:0xf
	v_fmac_f32_dpp v148, v181, v229 row_ror:2 row_mask:0xf bank_mask:0xf
	v_mul_f32_e32 v135, v135, v149
	v_add_f32_e32 v149, 1.0, v164
	v_mul_f32_e32 v163, 0xbfb8aa3b, v147
	v_mul_f32_e32 v164, 0xbfb8aa3b, v148
	v_rcp_f32_e32 v149, v149
	v_exp_f32_e32 v163, v163
	v_exp_f32_e32 v164, v164
	v_fmac_f32_dpp v160, v123, v91 row_shr:2 row_mask:0xf bank_mask:0xf bound_ctrl:1
	v_mul_f32_e32 v146, v146, v149
	v_add_f32_e32 v149, 1.0, v163
	v_add_f32_e32 v163, 1.0, v164
	v_rcp_f32_e32 v163, v163
	v_rcp_f32_e32 v149, v149
	v_fmac_f32_dpp v162, v125, v93 row_shr:2 row_mask:0xf bank_mask:0xf bound_ctrl:1
	v_fmac_f32_dpp v160, v179, v219 row_ror:1 row_mask:0xf bank_mask:0xf
	v_mul_f32_e32 v148, v148, v163
	v_fmac_f32_dpp v162, v177, v175 row_ror:1 row_mask:0xf bank_mask:0xf
	v_fmac_f32_dpp v160, v179, v221 row_ror:2 row_mask:0xf bank_mask:0xf
	v_mul_f32_e32 v147, v147, v149
	v_fmac_f32_dpp v162, v177, v213 row_ror:2 row_mask:0xf bank_mask:0xf
	v_mul_f32_e32 v146, v146, v160
	v_mul_f32_e32 v149, v148, v162
;     __device__ __forceinline__ void operator()(const f32x4 (&acc_)[2][2][4][2], const Unit& u, int wr, int wc, int fr_in, int fq_in) const {
;     ...
;                 for (int m = 0; m < 4; ++m) {
;                     f32x4 c[2];
; #pragma unroll
;                     for (int bj = 0; bj < 2; ++bj) {
;                         const f32x4 a = acc[ai][bj][m][n];
;                         f32x4 t1, t2;
;                         if (m > 0) { t1 = (f32x4){0.f, 0.f, 0.f, 0.f}; t2 = t1;
;                         } else {
;                             t1 = (f32x4){0.f, 0.f, 0.f, 0.f}; t2 = t1;
;                             const int sa = (wr == 1) ? ai : 0, sw = (wr == 1) ? 0 : 1;
;                             if ((wr == 1 || ai == 1) && fr < 2) {
;                                 const f32x4 h0 = halo[(((((sa * 2 + sw) * 2 + 0) * 4 + wc) * 2 + bj) * 4 + fq) * 2 + n], h1 = halo[(((((sa * 2 + sw) * 2 + 1) * 4 + wc) * 2 + bj) * 4 + fq) * 2 + n];
;                                 t1 = (fr == 0) ? h1 : (f32x4){0.f, 0.f, 0.f, 0.f}; t2 = (fr == 0) ? h0 : h1;
;                             }
;                         }
; #pragma unroll
;                         for (int i = 0; i < 4; ++i) {
;                             const float ax = a[i];
;                             float v = __builtin_fmaf(W2[bj][i], ax, Bb[bj][i]);
;                             PG8_FMAC_DPP(v, ax, W1[bj][i], "row_shr:1 row_mask:0xf bank_mask:0xf bound_ctrl:1");
;                             PG8_FMAC_DPP(v, ax, W0[bj][i], "row_shr:2 row_mask:0xf bank_mask:0xf bound_ctrl:1");
;                             if (m > 0) { const float apx = acc[ai][bj][m - 1][n][i];
;                                 PG8_FMAC_DPP(v, apx, W1m[bj][i], "row_ror:1 row_mask:0xf bank_mask:0xf");
;                                 PG8_FMAC_DPP(v, apx, W0m[bj][i], "row_ror:2 row_mask:0xf bank_mask:0xf");
;                             } else { v = __builtin_fmaf(t1[i], W1[bj][i], v); v = __builtin_fmaf(t2[i], W0[bj][i], v); }
;                             c[bj][i] = v;
;                         }
;                     }
;                     float hm[4];
; #pragma unroll
;                     for (int i = 0; i < 4; ++i) { const float g = c[0][i]; hm[i] = g * __builtin_amdgcn_rcpf(1.f + __builtin_amdgcn_exp2f(-1.4426950408889634f * g)) * c[1][i]; }
	v_cvt_pk_bf16_f32 v148, v135, v146
	v_fma_f32 v135, v110, v170, v82
	v_fmac_f32_dpp v135, v170, v106 row_shr:1 row_mask:0xf bank_mask:0xf bound_ctrl:1
	v_fmac_f32_dpp v161, v124, v96 row_shr:1 row_mask:0xf bank_mask:0xf bound_ctrl:1
	v_mov_b32_e32 v164, 0
	v_fmac_f32_dpp v135, v170, v102 row_shr:2 row_mask:0xf bank_mask:0xf bound_ctrl:1
	v_fmac_f32_dpp v161, v124, v92 row_shr:2 row_mask:0xf bank_mask:0xf bound_ctrl:1
	v_mov_b32_e32 v163, 0
	v_fmac_f32_dpp v135, v130, v246 row_ror:1 row_mask:0xf bank_mask:0xf
	v_fmac_f32_dpp v161, v176, v215 row_ror:1 row_mask:0xf bank_mask:0xf
	v_mov_b32_e32 v162, 0
	v_fmac_f32_dpp v135, v130, v203 row_ror:2 row_mask:0xf bank_mask:0xf
	v_fma_f32 v130, v111, v171, v83
	v_fmac_f32_dpp v130, v171, v107 row_shr:1 row_mask:0xf bank_mask:0xf bound_ctrl:1
	v_fmac_f32_dpp v161, v176, v217 row_ror:2 row_mask:0xf bank_mask:0xf
	s_nop 0
	v_fmac_f32_dpp v130, v171, v103 row_shr:2 row_mask:0xf bank_mask:0xf bound_ctrl:1
	v_mul_f32_e32 v147, v147, v161
	v_fmac_f32_dpp v130, v131, v237 row_ror:1 row_mask:0xf bank_mask:0xf
	v_cvt_pk_bf16_f32 v149, v147, v149
	v_mad_i64_i32 v[146:147], s[12:13], v220, s31, v[126:127]
	v_fmac_f32_dpp v130, v131, v245 row_ror:2 row_mask:0xf bank_mask:0xf
	v_fma_f32 v131, v112, v172, v84
	v_fmac_f32_dpp v131, v172, v108 row_shr:1 row_mask:0xf bank_mask:0xf bound_ctrl:1
	v_lshl_add_u64 v[146:147], v[146:147], 0, v[158:159]
	v_fmac_f32_dpp v131, v172, v104 row_shr:2 row_mask:0xf bank_mask:0xf bound_ctrl:1
	global_store_dwordx2 v[146:147], v[148:149], off
	v_fmac_f32_dpp v131, v128, v235 row_ror:1 row_mask:0xf bank_mask:0xf
	v_mul_f32_e32 v148, 0xbfb8aa3b, v135
	v_fmac_f32_dpp v131, v128, v236 row_ror:2 row_mask:0xf bank_mask:0xf
	v_fma_f32 v128, v113, v173, v85
	v_fmac_f32_dpp v128, v173, v109 row_shr:1 row_mask:0xf bank_mask:0xf bound_ctrl:1
	v_exp_f32_e32 v148, v148
	v_fmac_f32_dpp v128, v173, v105 row_shr:2 row_mask:0xf bank_mask:0xf bound_ctrl:1
	v_mul_f32_e32 v149, 0xbfb8aa3b, v130
	v_fmac_f32_dpp v128, v129, v223 row_ror:1 row_mask:0xf bank_mask:0xf
	v_add_f32_e32 v148, 1.0, v148
	v_fmac_f32_dpp v128, v129, v229 row_ror:2 row_mask:0xf bank_mask:0xf
	v_fma_f32 v129, v98, v166, v86
	v_fmac_f32_dpp v129, v166, v94 row_shr:1 row_mask:0xf bank_mask:0xf bound_ctrl:1
	v_rcp_f32_e32 v148, v148
	v_fmac_f32_dpp v129, v166, v90 row_shr:2 row_mask:0xf bank_mask:0xf bound_ctrl:1
	v_exp_f32_e32 v149, v149
	v_fmac_f32_dpp v129, v122, v226 row_ror:1 row_mask:0xf bank_mask:0xf
	v_mov_b32_e32 v161, 0
	v_fmac_f32_dpp v129, v122, v232 row_ror:2 row_mask:0xf bank_mask:0xf
	v_fma_f32 v122, v99, v167, v87
	v_fmac_f32_dpp v122, v167, v95 row_shr:1 row_mask:0xf bank_mask:0xf bound_ctrl:1
	s_nop 0
	v_fmac_f32_dpp v122, v167, v91 row_shr:2 row_mask:0xf bank_mask:0xf bound_ctrl:1
	s_nop 0
	v_fmac_f32_dpp v122, v123, v219 row_ror:1 row_mask:0xf bank_mask:0xf
	s_nop 0
	v_fmac_f32_dpp v122, v123, v221 row_ror:2 row_mask:0xf bank_mask:0xf
	v_fma_f32 v123, v100, v168, v88
	v_fmac_f32_dpp v123, v168, v96 row_shr:1 row_mask:0xf bank_mask:0xf bound_ctrl:1
	s_nop 0
	v_fmac_f32_dpp v123, v168, v92 row_shr:2 row_mask:0xf bank_mask:0xf bound_ctrl:1
	s_nop 0
	v_fmac_f32_dpp v123, v124, v215 row_ror:1 row_mask:0xf bank_mask:0xf
	s_nop 0
	v_fmac_f32_dpp v123, v124, v217 row_ror:2 row_mask:0xf bank_mask:0xf
	v_fma_f32 v124, v101, v169, v89
	v_fmac_f32_dpp v124, v169, v97 row_shr:1 row_mask:0xf bank_mask:0xf bound_ctrl:1
	s_nop 0
	v_fmac_f32_dpp v124, v169, v93 row_shr:2 row_mask:0xf bank_mask:0xf bound_ctrl:1
	s_nop 0
	v_fmac_f32_dpp v124, v125, v175 row_ror:1 row_mask:0xf bank_mask:0xf
	s_nop 0
	v_fmac_f32_dpp v124, v125, v213 row_ror:2 row_mask:0xf bank_mask:0xf
	v_mul_f32_e32 v125, v135, v148
	v_mul_f32_e32 v125, v125, v129
	v_add_f32_e32 v129, 1.0, v149
	v_mul_f32_e32 v135, 0xbfb8aa3b, v131
	v_mul_f32_e32 v148, 0xbfb8aa3b, v128
	v_rcp_f32_e32 v129, v129
	v_exp_f32_e32 v135, v135
	v_exp_f32_e32 v148, v148
	v_mul_f32_e32 v129, v130, v129
	v_add_f32_e32 v130, 1.0, v135
	v_add_f32_e32 v135, 1.0, v148
	v_rcp_f32_e32 v130, v130
	v_rcp_f32_e32 v135, v135
	v_mul_f32_e32 v122, v129, v122
	v_cvt_pk_bf16_f32 v122, v125, v122
	v_mul_f32_e32 v129, v131, v130
	v_mul_f32_e32 v128, v128, v135
	v_mul_f32_e32 v123, v129, v123
	v_mul_f32_e32 v124, v128, v124
	v_cvt_pk_bf16_f32 v123, v123, v124
	v_mad_i64_i32 v[124:125], s[12:13], v218, s31, v[126:127]
	v_lshl_add_u64 v[148:149], v[124:125], 0, v[158:159]
	global_store_dwordx2 v[148:149], v[122:123], off
	v_mov_b32_e32 v135, 0
	v_mov_b32_e32 v122, 0
	v_mov_b32_e32 v123, 0
	v_mov_b32_e32 v124, 0
	v_mov_b32_e32 v125, 0
	s_and_saveexec_b64 s[12:13], s[6:7]
	s_cbranch_execz .LBB0_1061
	v_add_u32_e32 v122, s68, v201
	ds_read_b128 v[126:129], v122 offset:1024
	v_mov_b32_e32 v161, 0
	v_mov_b32_e32 v162, 0
	v_mov_b32_e32 v163, 0
	v_mov_b32_e32 v164, 0
	s_waitcnt lgkmcnt(0)
	v_mov_b32_e32 v125, v129
	v_mov_b32_e32 v124, v128
	v_mov_b32_e32 v123, v127
	v_mov_b32_e32 v122, v126
	s_and_saveexec_b64 s[42:43], s[8:9]
	s_cbranch_execz .LBB0_1060
	v_add_u32_e32 v122, s64, v0
	ds_read_b128 v[122:125], v122
	v_mov_b32_e32 v161, v129
	v_mov_b32_e32 v162, v128
	v_mov_b32_e32 v163, v127
	v_mov_b32_e32 v164, v126

; __device__ __forceinline__ float rstd_of(const float* SSQ, size_t row) { const f32x4 s4 = *(const f32x4*)(SSQ + row * 4); return rsqrtf(((s4[0] + s4[1]) + (s4[2] + s4[3])) * (1.0f / 1024.0f) + 1e-6f); }
; #define SSQ WSL(float, WS_SSQ)
;     __device__ __forceinline__ void operator()(const f32x4 (&acc_)[2][2][4][2], const Unit& u, int wr, int wc, int fr_in, int fq_in) const {
;     ...
;             for (int m = 0; m < 4; ++m) { const float rs0 = rstd_of(SSQ, (size_t)(u.pm * BM + ai * HALF + wr * 64 + m * 16 + fr));
; #pragma unroll
;                 for (int bj = 0; bj < 2; ++bj)
; #pragma unroll
;                     for (int n = 0; n < 2; ++n) acc[ai][bj][m][n] = acc[ai][bj][m][n] * rs0; }
;     ...
;                 for (int m = 0; m < 4; ++m) {
;                     f32x4 c[2];
; #pragma unroll
;                     for (int bj = 0; bj < 2; ++bj) {
;                         const f32x4 a = acc[ai][bj][m][n];
;                         f32x4 t1, t2;
;                         if (m > 0) { t1 = (f32x4){0.f, 0.f, 0.f, 0.f}; t2 = t1;
;                         } else {
;                             t1 = (f32x4){0.f, 0.f, 0.f, 0.f}; t2 = t1;
;                             const int sa = (wr == 1) ? ai : 0, sw = (wr == 1) ? 0 : 1;
;                             if ((wr == 1 || ai == 1) && fr < 2) {
;                                 const f32x4 h0 = halo[(((((sa * 2 + sw) * 2 + 0) * 4 + wc) * 2 + bj) * 4 + fq) * 2 + n], h1 = halo[(((((sa * 2 + sw) * 2 + 1) * 4 + wc) * 2 + bj) * 4 + fq) * 2 + n];
;                                 t1 = (fr == 0) ? h1 : (f32x4){0.f, 0.f, 0.f, 0.f}; t2 = (fr == 0) ? h0 : h1;
;                             }
.LBB0_1061:
	s_or_b64 exec, exec, s[12:13]
	v_mov_b32_e32 v126, v155
	v_mov_b32_e32 v127, v156
	v_mov_b32_e32 v155, v157
	v_mov_b32_e32 v128, v151
	v_mov_b32_e32 v129, v152
	v_mov_b32_e32 v151, v153
	v_add_f32_e32 v126, v126, v154
	v_add_f32_e32 v127, v127, v155
	v_add_f32_e32 v128, v128, v150
	v_add_f32_e32 v129, v129, v151
	v_mov_b32_e32 v131, v126
	v_mov_b32_e32 v130, v128
	v_mov_b32_e32 v126, v129
	v_add_f32_e32 v126, v130, v126
	v_add_f32_e32 v127, v131, v127
	v_mov_b32_e32 v128, 0x358637bd
	v_pk_fma_f32 v[150:151], v[126:127], s[76:77], v[128:129] op_sel_hi:[1,0,0]
	s_mov_b32 s31, 0x800000
	v_mul_f32_e32 v126, 0x4b800000, v151
	v_cmp_gt_f32_e64 s[12:13], s31, v151
	v_cmp_gt_f32_e32 vcc, s31, v150
	v_mov_b32_e32 v167, 0
	v_cndmask_b32_e64 v126, v151, v126, s[12:13]
	v_rsq_f32_e32 v126, v126
	v_mov_b32_e32 v166, 0
	v_mov_b32_e32 v165, 0
	v_mul_f32_e32 v127, 0x45800000, v126
	v_cndmask_b32_e64 v130, v126, v127, s[12:13]
	v_mul_f32_e32 v152, v80, v130
	v_mul_f32_e32 v153, v81, v130
	v_mul_f32_e32 v154, v78, v130
	v_mul_f32_e32 v155, v79, v130
	v_fma_f32 v156, v112, v152, v84
	v_fma_f32 v157, v110, v154, v82
	v_fma_f32 v151, v111, v155, v83
	v_fma_f32 v160, v113, v153, v85
	v_fmac_f32_dpp v157, v154, v106 row_shr:1 row_mask:0xf bank_mask:0xf bound_ctrl:1
	v_fmac_f32_dpp v151, v155, v107 row_shr:1 row_mask:0xf bank_mask:0xf bound_ctrl:1
	v_fmac_f32_dpp v156, v152, v108 row_shr:1 row_mask:0xf bank_mask:0xf bound_ctrl:1
	v_fmac_f32_dpp v160, v153, v109 row_shr:1 row_mask:0xf bank_mask:0xf bound_ctrl:1
	v_mov_b32_e32 v78, 0
	v_mov_b32_e32 v79, 0
	v_mov_b32_e32 v80, 0
	v_mov_b32_e32 v81, 0
	v_fmac_f32_dpp v157, v154, v102 row_shr:2 row_mask:0xf bank_mask:0xf bound_ctrl:1
	v_fmac_f32_dpp v151, v155, v103 row_shr:2 row_mask:0xf bank_mask:0xf bound_ctrl:1
	v_fmac_f32_dpp v156, v152, v104 row_shr:2 row_mask:0xf bank_mask:0xf bound_ctrl:1
	v_fmac_f32_dpp v160, v153, v105 row_shr:2 row_mask:0xf bank_mask:0xf bound_ctrl:1
	s_and_saveexec_b64 s[12:13], s[6:7]
	s_cbranch_execz .LBB0_1065
	v_add_u32_e32 v78, s65, v0
	ds_read_b128 v[126:129], v78 offset:1024
	v_mov_b32_e32 v165, 0
	v_mov_b32_e32 v166, 0
	v_mov_b32_e32 v167, 0
	v_mov_b32_e32 v135, 0
	s_waitcnt lgkmcnt(0)
	v_mov_b32_e32 v81, v129
	v_mov_b32_e32 v80, v128
	v_mov_b32_e32 v79, v127
	v_mov_b32_e32 v78, v126
	s_and_saveexec_b64 s[42:43], s[8:9]
	s_cbranch_execz .LBB0_1064
	v_add_u32_e32 v78, s64, v0
	ds_read_b128 v[78:81], v78 offset:128
	v_mov_b32_e32 v165, v129
	v_mov_b32_e32 v166, v128
	v_mov_b32_e32 v167, v127
	v_mov_b32_e32 v135, v126

;     __device__ __forceinline__ void operator()(const f32x4 (&acc_)[2][2][4][2], const Unit& u, int wr, int wc, int fr_in, int fq_in) const {
;     ...
;             for (int m = 0; m < 4; ++m) { const float rs0 = rstd_of(SSQ, (size_t)(u.pm * BM + ai * HALF + wr * 64 + m * 16 + fr));
; #pragma unroll
;                 for (int bj = 0; bj < 2; ++bj)
; #pragma unroll
;                     for (int n = 0; n < 2; ++n) acc[ai][bj][m][n] = acc[ai][bj][m][n] * rs0; }
;     ...
;         for (int n = 0; n < 2; ++n) {
;             f32x4 W0[2], W1[2], W2[2], Bb[2], W0m[2], W1m[2];
; #pragma unroll
;             for (int bj = 0; bj < 2; ++bj) { const float* wp = cw + bj * 2816 + jcol + 4 * n;
;                 if (n == 0) { W0[bj] = Wn[bj][0]; W1[bj] = Wn[bj][1]; W2[bj] = Wn[bj][2]; Bb[bj] = Wn[bj][3]; }
;                 else { W0[bj] = *(const f32x4*)(wp); W1[bj] = *(const f32x4*)(wp + 5632); W2[bj] = *(const f32x4*)(wp + 2 * 5632); Bb[bj] = *(const f32x4*)(cb + bj * 2816 + jcol + 4 * n); }
;                 W1m[bj] = fr == 0 ? W1[bj] : (f32x4){0.f, 0.f, 0.f, 0.f}; W0m[bj] = fr < 2 ? W0[bj] : (f32x4){0.f, 0.f, 0.f, 0.f}; }
; #pragma unroll
;             for (int ai = 0; ai < 2; ++ai)
; #pragma unroll
;                 for (int m = 0; m < 4; ++m) {
;                     f32x4 c[2];
; #pragma unroll
;                     for (int bj = 0; bj < 2; ++bj) {
;                         const f32x4 a = acc[ai][bj][m][n];
;                         f32x4 t1, t2;
;                         if (m > 0) { t1 = (f32x4){0.f, 0.f, 0.f, 0.f}; t2 = t1;
;                         } else {
;                             t1 = (f32x4){0.f, 0.f, 0.f, 0.f}; t2 = t1;
;                             const int sa = (wr == 1) ? ai : 0, sw = (wr == 1) ? 0 : 1;
;                             if ((wr == 1 || ai == 1) && fr < 2) {
;                                 const f32x4 h0 = halo[(((((sa * 2 + sw) * 2 + 0) * 4 + wc) * 2 + bj) * 4 + fq) * 2 + n], h1 = halo[(((((sa * 2 + sw) * 2 + 1) * 4 + wc) * 2 + bj) * 4 + fq) * 2 + n];
;                                 t1 = (fr == 0) ? h1 : (f32x4){0.f, 0.f, 0.f, 0.f}; t2 = (fr == 0) ? h0 : h1;
;                             }
;                         }
; #pragma unroll
;                         for (int i = 0; i < 4; ++i) {
;                             const float ax = a[i];
;                             float v = __builtin_fmaf(W2[bj][i], ax, Bb[bj][i]);
.LBB0_1065:
	s_or_b64 exec, exec, s[12:13]
	v_fmac_f32_e32 v151, v163, v107
	s_waitcnt lgkmcnt(0)
	v_fmac_f32_e32 v151, v123, v103
	v_mul_f32_e32 v123, 0x4b800000, v150
	v_fmac_f32_e32 v156, v162, v108
	v_cndmask_b32_e32 v123, v150, v123, vcc
	v_fmac_f32_e32 v156, v124, v104
	v_rsq_f32_e32 v124, v123
	v_mov_b32_e32 v131, v130
	v_fmac_f32_e32 v157, v164, v106
	v_fmac_f32_e32 v157, v122, v102
	v_mov_b32_e32 v122, v130
	v_mov_b32_e32 v123, v130
	v_pk_mul_f32 v[128:129], v[70:71], v[130:131]
	v_mul_f32_e32 v70, 0x45800000, v124
	v_pk_mul_f32 v[126:127], v[72:73], v[122:123]
	v_cndmask_b32_e32 v122, v124, v70, vcc
	v_mul_f32_e32 v70, 0x4b800000, v227
	v_cndmask_b32_e64 v70, v227, v70, s[10:11]
	v_mul_f32_e32 v76, v76, v122
	v_mul_f32_e32 v77, v77, v122
	v_rsq_f32_e32 v123, v70
	v_fmac_f32_e32 v160, v161, v109
	v_fmac_f32_e32 v160, v125, v105
	s_movk_i32 s12, 0x1600
	v_mul_f32_e32 v72, v62, v122
	v_mul_f32_e32 v73, v63, v122
	v_mul_f32_e32 v62, 0x45800000, v123
	v_cndmask_b32_e64 v150, v123, v62, s[10:11]
	v_fma_f32 v62, v98, v128, v86
	v_fmac_f32_dpp v62, v128, v94 row_shr:1 row_mask:0xf bank_mask:0xf bound_ctrl:1
	v_fma_f32 v63, v99, v129, v87
	v_fmac_f32_dpp v62, v128, v90 row_shr:2 row_mask:0xf bank_mask:0xf bound_ctrl:1
	v_fmac_f32_dpp v63, v129, v95 row_shr:1 row_mask:0xf bank_mask:0xf bound_ctrl:1
	v_mul_f32_e32 v70, v64, v122
	v_mul_f32_e32 v71, v65, v122
	v_fmac_f32_e32 v62, v135, v94
	v_fmac_f32_e32 v62, v78, v90
	v_mul_f32_e32 v78, 0xbfb8aa3b, v157
	v_exp_f32_e32 v78, v78
	v_fmac_f32_dpp v63, v129, v91 row_shr:2 row_mask:0xf bank_mask:0xf bound_ctrl:1
	v_mul_f32_e32 v64, v68, v150
	v_mul_f32_e32 v65, v69, v150
	v_fmac_f32_e32 v63, v167, v95
	v_add_f32_e32 v78, 1.0, v78
	v_fmac_f32_e32 v63, v79, v91
	v_rcp_f32_e32 v78, v78
	v_mul_f32_e32 v79, 0xbfb8aa3b, v151
	v_exp_f32_e32 v79, v79
	v_fma_f32 v68, v100, v126, v88
	v_fmac_f32_dpp v68, v126, v96 row_shr:1 row_mask:0xf bank_mask:0xf bound_ctrl:1
	v_mul_f32_e32 v78, v157, v78
	v_fmac_f32_dpp v68, v126, v92 row_shr:2 row_mask:0xf bank_mask:0xf bound_ctrl:1
	v_mul_f32_e32 v62, v78, v62
	v_fmac_f32_e32 v68, v166, v96
	v_add_f32_e32 v78, 1.0, v79
	v_mul_f32_e32 v79, 0xbfb8aa3b, v156
	v_fmac_f32_e32 v68, v80, v92
	v_exp_f32_e32 v79, v79
	v_mul_f32_e32 v80, 0xbfb8aa3b, v160
	v_exp_f32_e32 v80, v80
	v_rcp_f32_e32 v78, v78
	v_add_f32_e32 v79, 1.0, v79
	v_rcp_f32_e32 v79, v79
	v_add_f32_e32 v80, 1.0, v80
	v_fma_f32 v69, v101, v127, v89
	v_rcp_f32_e32 v80, v80
	v_fmac_f32_dpp v69, v127, v97 row_shr:1 row_mask:0xf bank_mask:0xf bound_ctrl:1
	v_mul_f32_e32 v78, v151, v78
	v_fmac_f32_dpp v69, v127, v93 row_shr:2 row_mask:0xf bank_mask:0xf bound_ctrl:1
	v_mul_f32_e32 v63, v78, v63
	v_fmac_f32_e32 v69, v165, v97
	v_mul_f32_e32 v78, v156, v79
	v_fmac_f32_e32 v69, v81, v93
	v_mul_f32_e32 v78, v78, v68
	v_mul_f32_e32 v68, v160, v80
	v_mul_f32_e32 v69, v68, v69
	v_cvt_pk_bf16_f32 v68, v62, v63
	v_mov_b64_e32 v[62:63], s[20:21]
	v_cvt_pk_bf16_f32 v69, v78, v69
	v_mad_i64_i32 v[78:79], s[10:11], v216, s12, v[62:63]
	v_mul_f32_e32 v74, v74, v122
	v_mul_f32_e32 v75, v75, v122
	v_lshl_add_u64 v[124:125], v[78:79], 0, v[158:159]
	global_store_dwordx2 v[124:125], v[68:69], off
	v_fma_f32 v68, v110, v74, v82
	v_fma_f32 v80, v98, v72, v86
	v_fmac_f32_dpp v68, v74, v106 row_shr:1 row_mask:0xf bank_mask:0xf bound_ctrl:1
	v_fmac_f32_dpp v80, v72, v94 row_shr:1 row_mask:0xf bank_mask:0xf bound_ctrl:1
	v_fma_f32 v69, v111, v75, v83
	v_fmac_f32_dpp v68, v74, v102 row_shr:2 row_mask:0xf bank_mask:0xf bound_ctrl:1
	v_fmac_f32_dpp v80, v72, v90 row_shr:2 row_mask:0xf bank_mask:0xf bound_ctrl:1
	v_fma_f32 v81, v99, v73, v87
	v_fmac_f32_dpp v68, v154, v246 row_ror:1 row_mask:0xf bank_mask:0xf
	v_fmac_f32_dpp v80, v128, v226 row_ror:1 row_mask:0xf bank_mask:0xf
	v_fmac_f32_dpp v69, v75, v107 row_shr:1 row_mask:0xf bank_mask:0xf bound_ctrl:1
	v_fmac_f32_dpp v81, v73, v95 row_shr:1 row_mask:0xf bank_mask:0xf bound_ctrl:1
	v_fma_f32 v123, v100, v70, v88
	v_fmac_f32_dpp v68, v154, v203 row_ror:2 row_mask:0xf bank_mask:0xf
	v_fmac_f32_dpp v80, v128, v232 row_ror:2 row_mask:0xf bank_mask:0xf
	v_fmac_f32_dpp v69, v75, v103 row_shr:2 row_mask:0xf bank_mask:0xf bound_ctrl:1
	v_fmac_f32_dpp v81, v73, v91 row_shr:2 row_mask:0xf bank_mask:0xf bound_ctrl:1
	v_fmac_f32_dpp v123, v70, v96 row_shr:1 row_mask:0xf bank_mask:0xf bound_ctrl:1
	v_fma_f32 v78, v112, v76, v84
	v_mul_f32_e32 v128, 0xbfb8aa3b, v68
	v_exp_f32_e32 v128, v128
	v_fmac_f32_dpp v69, v155, v237 row_ror:1 row_mask:0xf bank_mask:0xf
	v_fmac_f32_dpp v81, v129, v219 row_ror:1 row_mask:0xf bank_mask:0xf
	v_fmac_f32_dpp v123, v70, v92 row_shr:2 row_mask:0xf bank_mask:0xf bound_ctrl:1
	v_fma_f32 v79, v113, v77, v85
	v_add_f32_e32 v128, 1.0, v128
	v_fmac_f32_dpp v69, v155, v245 row_ror:2 row_mask:0xf bank_mask:0xf
	v_fmac_f32_dpp v81, v129, v221 row_ror:2 row_mask:0xf bank_mask:0xf
	v_fmac_f32_dpp v123, v126, v215 row_ror:1 row_mask:0xf bank_mask:0xf
	v_rcp_f32_e32 v128, v128
	v_mul_f32_e32 v129, 0xbfb8aa3b, v69
	v_fmac_f32_dpp v123, v126, v217 row_ror:2 row_mask:0xf bank_mask:0xf
	v_fma_f32 v126, v101, v71, v89
	v_exp_f32_e32 v129, v129
	v_fmac_f32_dpp v78, v76, v108 row_shr:1 row_mask:0xf bank_mask:0xf bound_ctrl:1
	v_fmac_f32_dpp v79, v77, v109 row_shr:1 row_mask:0xf bank_mask:0xf bound_ctrl:1
	v_fmac_f32_dpp v126, v71, v97 row_shr:1 row_mask:0xf bank_mask:0xf bound_ctrl:1
	v_mul_f32_e32 v68, v68, v128
	v_fmac_f32_dpp v78, v76, v104 row_shr:2 row_mask:0xf bank_mask:0xf bound_ctrl:1
	v_fmac_f32_dpp v79, v77, v105 row_shr:2 row_mask:0xf bank_mask:0xf bound_ctrl:1
	v_fmac_f32_dpp v126, v71, v93 row_shr:2 row_mask:0xf bank_mask:0xf bound_ctrl:1
	v_mul_f32_e32 v68, v68, v80
;     __device__ __forceinline__ void operator()(const f32x4 (&acc_)[2][2][4][2], const Unit& u, int wr, int wc, int fr_in, int fq_in) const {
;     ...
;                 for (int m = 0; m < 4; ++m) {
;                     f32x4 c[2];
; #pragma unroll
;                     for (int bj = 0; bj < 2; ++bj) {
;                         const f32x4 a = acc[ai][bj][m][n];
;                         f32x4 t1, t2;
;                         if (m > 0) { t1 = (f32x4){0.f, 0.f, 0.f, 0.f}; t2 = t1;
;                         } else {
;                             t1 = (f32x4){0.f, 0.f, 0.f, 0.f}; t2 = t1;
;                             const int sa = (wr == 1) ? ai : 0, sw = (wr == 1) ? 0 : 1;
;                             if ((wr == 1 || ai == 1) && fr < 2) {
;                                 const f32x4 h0 = halo[(((((sa * 2 + sw) * 2 + 0) * 4 + wc) * 2 + bj) * 4 + fq) * 2 + n], h1 = halo[(((((sa * 2 + sw) * 2 + 1) * 4 + wc) * 2 + bj) * 4 + fq) * 2 + n];
;                                 t1 = (fr == 0) ? h1 : (f32x4){0.f, 0.f, 0.f, 0.f}; t2 = (fr == 0) ? h0 : h1;
;                             }
;                         }
; #pragma unroll
;                         for (int i = 0; i < 4; ++i) {
;                             const float ax = a[i];
;                             float v = __builtin_fmaf(W2[bj][i], ax, Bb[bj][i]);
;                             PG8_FMAC_DPP(v, ax, W1[bj][i], "row_shr:1 row_mask:0xf bank_mask:0xf bound_ctrl:1");
;                             PG8_FMAC_DPP(v, ax, W0[bj][i], "row_shr:2 row_mask:0xf bank_mask:0xf bound_ctrl:1");
;                             if (m > 0) { const float apx = acc[ai][bj][m - 1][n][i];
;                                 PG8_FMAC_DPP(v, apx, W1m[bj][i], "row_ror:1 row_mask:0xf bank_mask:0xf");
;                                 PG8_FMAC_DPP(v, apx, W0m[bj][i], "row_ror:2 row_mask:0xf bank_mask:0xf");
;                             } else { v = __builtin_fmaf(t1[i], W1[bj][i], v); v = __builtin_fmaf(t2[i], W0[bj][i], v); }
;                             c[bj][i] = v;
;                         }
;                     }
;                     float hm[4];
; #pragma unroll
;                     for (int i = 0; i < 4; ++i) { const float g = c[0][i]; hm[i] = g * __builtin_amdgcn_rcpf(1.f + __builtin_amdgcn_exp2f(-1.4426950408889634f * g)) * c[1][i]; }
	v_fmac_f32_dpp v78, v152, v235 row_ror:1 row_mask:0xf bank_mask:0xf
	v_fmac_f32_dpp v79, v153, v223 row_ror:1 row_mask:0xf bank_mask:0xf
	v_fmac_f32_dpp v126, v127, v175 row_ror:1 row_mask:0xf bank_mask:0xf
	v_add_f32_e32 v80, 1.0, v129
	v_fmac_f32_dpp v78, v152, v236 row_ror:2 row_mask:0xf bank_mask:0xf
	v_fmac_f32_dpp v79, v153, v229 row_ror:2 row_mask:0xf bank_mask:0xf
	v_fmac_f32_dpp v126, v127, v213 row_ror:2 row_mask:0xf bank_mask:0xf
	v_rcp_f32_e32 v80, v80
	v_mul_f32_e32 v127, 0xbfb8aa3b, v78
	v_mul_f32_e32 v128, 0xbfb8aa3b, v79
	v_exp_f32_e32 v127, v127
	v_exp_f32_e32 v128, v128
	v_mul_f32_e32 v69, v69, v80
	v_mul_f32_e32 v69, v69, v81
	v_add_f32_e32 v80, 1.0, v127
	v_add_f32_e32 v127, 1.0, v128
	v_rcp_f32_e32 v80, v80
	v_rcp_f32_e32 v127, v127
	v_cvt_pk_bf16_f32 v68, v68, v69
	v_mul_f32_e32 v66, v66, v150
	v_mul_f32_e32 v67, v67, v150
	v_mul_f32_e32 v78, v78, v80
	v_mul_f32_e32 v79, v79, v127
	v_mul_f32_e32 v78, v78, v123
	v_mul_f32_e32 v79, v79, v126
	v_cvt_pk_bf16_f32 v69, v78, v79
	v_mad_i64_i32 v[78:79], s[10:11], v212, s12, v[62:63]
	v_lshl_add_u64 v[126:127], v[78:79], 0, v[158:159]
	global_store_dwordx2 v[126:127], v[68:69], off
	v_fma_f32 v68, v110, v66, v82
	v_fmac_f32_dpp v68, v66, v106 row_shr:1 row_mask:0xf bank_mask:0xf bound_ctrl:1
	v_fma_f32 v69, v111, v67, v83
	v_fmac_f32_dpp v68, v66, v102 row_shr:2 row_mask:0xf bank_mask:0xf bound_ctrl:1
	v_fmac_f32_dpp v69, v67, v107 row_shr:1 row_mask:0xf bank_mask:0xf bound_ctrl:1
	v_mul_f32_e32 v58, v58, v150
	v_mul_f32_e32 v59, v59, v150
	v_fmac_f32_dpp v68, v74, v246 row_ror:1 row_mask:0xf bank_mask:0xf
	v_fmac_f32_dpp v69, v67, v103 row_shr:2 row_mask:0xf bank_mask:0xf bound_ctrl:1
	v_mul_f32_e32 v60, v60, v150
	v_mul_f32_e32 v61, v61, v150
	v_fmac_f32_dpp v68, v74, v203 row_ror:2 row_mask:0xf bank_mask:0xf
	v_fma_f32 v74, v112, v64, v84
	v_fmac_f32_dpp v74, v64, v108 row_shr:1 row_mask:0xf bank_mask:0xf bound_ctrl:1
	v_fmac_f32_dpp v69, v75, v237 row_ror:1 row_mask:0xf bank_mask:0xf
	s_nop 0
	v_fmac_f32_dpp v74, v64, v104 row_shr:2 row_mask:0xf bank_mask:0xf bound_ctrl:1
	v_fmac_f32_dpp v69, v75, v245 row_ror:2 row_mask:0xf bank_mask:0xf
	v_fma_f32 v75, v113, v65, v85
	v_fmac_f32_dpp v74, v76, v235 row_ror:1 row_mask:0xf bank_mask:0xf
	v_fmac_f32_dpp v75, v65, v109 row_shr:1 row_mask:0xf bank_mask:0xf bound_ctrl:1
	v_mul_f32_e32 v78, 0xbfb8aa3b, v69
	v_fmac_f32_dpp v74, v76, v236 row_ror:2 row_mask:0xf bank_mask:0xf
	v_fma_f32 v76, v98, v58, v86
	v_fmac_f32_dpp v76, v58, v94 row_shr:1 row_mask:0xf bank_mask:0xf bound_ctrl:1
	v_fmac_f32_dpp v75, v65, v105 row_shr:2 row_mask:0xf bank_mask:0xf bound_ctrl:1
	v_exp_f32_e32 v78, v78
	v_fmac_f32_dpp v76, v58, v90 row_shr:2 row_mask:0xf bank_mask:0xf bound_ctrl:1
	v_fmac_f32_dpp v75, v77, v223 row_ror:1 row_mask:0xf bank_mask:0xf
	v_fmac_f32_e32 v85, v113, v145
	v_fmac_f32_dpp v76, v72, v226 row_ror:1 row_mask:0xf bank_mask:0xf
	v_fmac_f32_dpp v75, v77, v229 row_ror:2 row_mask:0xf bank_mask:0xf
	v_mul_f32_e32 v77, 0xbfb8aa3b, v68
	v_fmac_f32_dpp v76, v72, v232 row_ror:2 row_mask:0xf bank_mask:0xf
	v_fma_f32 v72, v99, v59, v87
	v_fmac_f32_dpp v72, v59, v95 row_shr:1 row_mask:0xf bank_mask:0xf bound_ctrl:1
	v_exp_f32_e32 v77, v77
	v_fmac_f32_dpp v72, v59, v91 row_shr:2 row_mask:0xf bank_mask:0xf bound_ctrl:1
	v_fmac_f32_dpp v85, v145, v109 row_shr:1 row_mask:0xf bank_mask:0xf bound_ctrl:1
	s_nop 0
	v_fmac_f32_dpp v72, v73, v219 row_ror:1 row_mask:0xf bank_mask:0xf
	v_add_f32_e32 v77, 1.0, v77
	v_fmac_f32_dpp v72, v73, v221 row_ror:2 row_mask:0xf bank_mask:0xf
	v_fma_f32 v73, v100, v60, v88
	v_fmac_f32_dpp v73, v60, v96 row_shr:1 row_mask:0xf bank_mask:0xf bound_ctrl:1
	v_rcp_f32_e32 v77, v77
	v_fmac_f32_dpp v73, v60, v92 row_shr:2 row_mask:0xf bank_mask:0xf bound_ctrl:1
	v_fmac_f32_dpp v85, v145, v105 row_shr:2 row_mask:0xf bank_mask:0xf bound_ctrl:1
	v_mov_b32_e32 v105, 0
	v_fmac_f32_dpp v73, v70, v215 row_ror:1 row_mask:0xf bank_mask:0xf
	v_mul_f32_e32 v68, v68, v77
	v_fmac_f32_dpp v73, v70, v217 row_ror:2 row_mask:0xf bank_mask:0xf
	v_fma_f32 v70, v101, v61, v89
	v_fmac_f32_dpp v70, v61, v97 row_shr:1 row_mask:0xf bank_mask:0xf bound_ctrl:1
	v_mul_f32_e32 v68, v68, v76
	v_fmac_f32_dpp v70, v61, v93 row_shr:2 row_mask:0xf bank_mask:0xf bound_ctrl:1
	v_mul_f32_e32 v76, 0xbfb8aa3b, v74
	v_fmac_f32_dpp v70, v71, v175 row_ror:1 row_mask:0xf bank_mask:0xf
	v_mul_f32_e32 v77, 0xbfb8aa3b, v75
	v_fmac_f32_dpp v70, v71, v213 row_ror:2 row_mask:0xf bank_mask:0xf
	v_add_f32_e32 v71, 1.0, v78
	v_rcp_f32_e32 v71, v71
	v_exp_f32_e32 v76, v76
	v_exp_f32_e32 v77, v77
	v_fmac_f32_dpp v85, v65, v223 row_ror:1 row_mask:0xf bank_mask:0xf
	v_mul_f32_e32 v69, v69, v71
	v_add_f32_e32 v71, 1.0, v76
	v_add_f32_e32 v76, 1.0, v77
	v_rcp_f32_e32 v71, v71
	v_rcp_f32_e32 v76, v76
	v_mul_f32_e32 v69, v69, v72
	v_cvt_pk_bf16_f32 v68, v68, v69
	v_mul_f32_e32 v71, v74, v71
	v_mul_f32_e32 v72, v75, v76
	v_mul_f32_e32 v71, v71, v73
	v_mul_f32_e32 v70, v72, v70
	v_cvt_pk_bf16_f32 v69, v71, v70
	v_mad_i64_i32 v[70:71], s[10:11], v214, s12, v[62:63]
	v_lshl_add_u64 v[128:129], v[70:71], 0, v[158:159]
;     __device__ __forceinline__ void operator()(const f32x4 (&acc_)[2][2][4][2], const Unit& u, int wr, int wc, int fr_in, int fq_in) const {
;     ...
;             for (int bj = 0; bj < 2; ++bj) { const float* wp = cw + bj * 2816 + jcol + 4 * n;
;                 if (n == 0) { W0[bj] = Wn[bj][0]; W1[bj] = Wn[bj][1]; W2[bj] = Wn[bj][2]; Bb[bj] = Wn[bj][3]; }
;                 else { W0[bj] = *(const f32x4*)(wp); W1[bj] = *(const f32x4*)(wp + 5632); W2[bj] = *(const f32x4*)(wp + 2 * 5632); Bb[bj] = *(const f32x4*)(cb + bj * 2816 + jcol + 4 * n); }
;                 W1m[bj] = fr == 0 ? W1[bj] : (f32x4){0.f, 0.f, 0.f, 0.f}; W0m[bj] = fr < 2 ? W0[bj] : (f32x4){0.f, 0.f, 0.f, 0.f}; }
; #pragma unroll
;             for (int ai = 0; ai < 2; ++ai)
; #pragma unroll
;                 for (int m = 0; m < 4; ++m) {
;                     f32x4 c[2];
; #pragma unroll
;                     for (int bj = 0; bj < 2; ++bj) {
;                         const f32x4 a = acc[ai][bj][m][n];
;                         f32x4 t1, t2;
;                         if (m > 0) { t1 = (f32x4){0.f, 0.f, 0.f, 0.f}; t2 = t1;
;                         } else {
;                             t1 = (f32x4){0.f, 0.f, 0.f, 0.f}; t2 = t1;
;                             const int sa = (wr == 1) ? ai : 0, sw = (wr == 1) ? 0 : 1;
;                             if ((wr == 1 || ai == 1) && fr < 2) {
;                                 const f32x4 h0 = halo[(((((sa * 2 + sw) * 2 + 0) * 4 + wc) * 2 + bj) * 4 + fq) * 2 + n], h1 = halo[(((((sa * 2 + sw) * 2 + 1) * 4 + wc) * 2 + bj) * 4 + fq) * 2 + n];
;                                 t1 = (fr == 0) ? h1 : (f32x4){0.f, 0.f, 0.f, 0.f}; t2 = (fr == 0) ? h0 : h1;
;                             }
	global_store_dwordx2 v[128:129], v[68:69], off
	v_fma_f32 v68, v110, v142, v82
	v_fmac_f32_dpp v68, v142, v106 row_shr:1 row_mask:0xf bank_mask:0xf bound_ctrl:1
	v_fmac_f32_dpp v85, v65, v229 row_ror:2 row_mask:0xf bank_mask:0xf
	v_fmac_f32_e32 v89, v101, v141
	v_fmac_f32_dpp v68, v142, v102 row_shr:2 row_mask:0xf bank_mask:0xf bound_ctrl:1
	v_fmac_f32_dpp v89, v141, v97 row_shr:1 row_mask:0xf bank_mask:0xf bound_ctrl:1
	v_mov_b32_e32 v106, 0
	v_fmac_f32_dpp v68, v66, v246 row_ror:1 row_mask:0xf bank_mask:0xf
	v_fmac_f32_dpp v89, v141, v93 row_shr:2 row_mask:0xf bank_mask:0xf bound_ctrl:1
	v_mov_b32_e32 v141, 0
	v_fmac_f32_dpp v68, v66, v203 row_ror:2 row_mask:0xf bank_mask:0xf
	v_fma_f32 v66, v111, v143, v83
	v_fmac_f32_dpp v66, v143, v107 row_shr:1 row_mask:0xf bank_mask:0xf bound_ctrl:1
	v_fmac_f32_dpp v89, v61, v175 row_ror:1 row_mask:0xf bank_mask:0xf
	v_mov_b32_e32 v107, 0
	v_fmac_f32_dpp v66, v143, v103 row_shr:2 row_mask:0xf bank_mask:0xf bound_ctrl:1
	v_fmac_f32_dpp v89, v61, v213 row_ror:2 row_mask:0xf bank_mask:0xf
	v_mov_b32_e32 v93, 0
	v_fmac_f32_dpp v66, v67, v237 row_ror:1 row_mask:0xf bank_mask:0xf
	s_nop 0
	v_fmac_f32_dpp v66, v67, v245 row_ror:2 row_mask:0xf bank_mask:0xf
	v_fma_f32 v67, v112, v144, v84
	v_fmac_f32_dpp v67, v144, v108 row_shr:1 row_mask:0xf bank_mask:0xf bound_ctrl:1
	v_mul_f32_e32 v65, 0xbfb8aa3b, v66
	v_fmac_f32_dpp v67, v144, v104 row_shr:2 row_mask:0xf bank_mask:0xf bound_ctrl:1
	v_exp_f32_e32 v65, v65
	v_fmac_f32_dpp v67, v64, v235 row_ror:1 row_mask:0xf bank_mask:0xf
	v_mov_b32_e32 v104, 0
	v_fmac_f32_dpp v67, v64, v236 row_ror:2 row_mask:0xf bank_mask:0xf
	v_fma_f32 v64, v98, v138, v86
	v_fmac_f32_dpp v64, v138, v94 row_shr:1 row_mask:0xf bank_mask:0xf bound_ctrl:1
	v_add_f32_e32 v61, 1.0, v65
	v_fmac_f32_dpp v64, v138, v90 row_shr:2 row_mask:0xf bank_mask:0xf bound_ctrl:1
	v_mul_f32_e32 v65, 0xbfb8aa3b, v85
	v_fmac_f32_dpp v64, v58, v226 row_ror:1 row_mask:0xf bank_mask:0xf
	v_exp_f32_e32 v65, v65
	v_fmac_f32_dpp v64, v58, v232 row_ror:2 row_mask:0xf bank_mask:0xf
	v_fma_f32 v58, v99, v139, v87
	v_fmac_f32_dpp v58, v139, v95 row_shr:1 row_mask:0xf bank_mask:0xf bound_ctrl:1
	v_rcp_f32_e32 v61, v61
	v_fmac_f32_dpp v58, v139, v91 row_shr:2 row_mask:0xf bank_mask:0xf bound_ctrl:1
	v_add_f32_e32 v65, 1.0, v65
	v_fmac_f32_dpp v58, v59, v219 row_ror:1 row_mask:0xf bank_mask:0xf
	v_rcp_f32_e32 v65, v65
	v_fmac_f32_dpp v58, v59, v221 row_ror:2 row_mask:0xf bank_mask:0xf
	v_fma_f32 v59, v100, v140, v88
	v_fmac_f32_dpp v59, v140, v96 row_shr:1 row_mask:0xf bank_mask:0xf bound_ctrl:1
	v_mul_f32_e32 v61, v66, v61
	v_fmac_f32_dpp v59, v140, v92 row_shr:2 row_mask:0xf bank_mask:0xf bound_ctrl:1
	v_mul_f32_e32 v58, v61, v58
	v_fmac_f32_dpp v59, v60, v215 row_ror:1 row_mask:0xf bank_mask:0xf
	v_mov_b32_e32 v90, 0
	v_fmac_f32_dpp v59, v60, v217 row_ror:2 row_mask:0xf bank_mask:0xf
	v_mul_f32_e32 v60, 0xbfb8aa3b, v68
	v_exp_f32_e32 v60, v60
	v_mov_b32_e32 v91, 0
	v_mov_b32_e32 v92, 0
	v_add_f32_e32 v60, 1.0, v60
	v_rcp_f32_e32 v60, v60
	s_nop 0
	v_mul_f32_e32 v60, v68, v60
	v_mul_f32_e32 v60, v60, v64
	v_mul_f32_e32 v64, 0xbfb8aa3b, v67
	v_exp_f32_e32 v64, v64
	v_cvt_pk_bf16_f32 v58, v60, v58
	s_nop 0
	v_add_f32_e32 v64, 1.0, v64
	v_rcp_f32_e32 v64, v64
	s_nop 0
	v_mul_f32_e32 v61, v67, v64
	v_mul_f32_e32 v59, v61, v59
	v_mul_f32_e32 v61, v85, v65
	v_mul_f32_e32 v61, v61, v89
	v_cvt_pk_bf16_f32 v59, v59, v61
	v_mad_i64_i32 v[60:61], s[10:11], v200, s12, v[62:63]
	v_lshl_add_u64 v[102:103], v[60:61], 0, v[158:159]
	global_store_dwordx2 v[102:103], v[58:59], off
	v_add_co_u32_e32 v58, vcc, 0x5000, v196
	global_load_dwordx4 v[78:81], v[196:197], off offset:16
	s_nop 0
	v_addc_co_u32_e32 v59, vcc, 0, v197, vcc
	v_add_co_u32_e32 v60, vcc, 0xb000, v196
	s_nop 1
	v_addc_co_u32_e32 v61, vcc, 0, v197, vcc
	v_add_co_u32_e32 v62, vcc, 0x8000, v196
	global_load_dwordx4 v[82:85], v[58:59], off offset:2064
	global_load_dwordx4 v[86:89], v[60:61], off offset:16
	s_nop 0
	global_load_dwordx4 v[58:61], v[194:195], off offset:16
	v_addc_co_u32_e32 v63, vcc, 0, v197, vcc
	global_load_dwordx4 v[66:69], v[198:199], off offset:3088
	global_load_dwordx4 v[70:73], v[62:63], off offset:1040
	v_add_co_u32_e32 v62, vcc, 0xd000, v196
	s_nop 1
	v_addc_co_u32_e32 v63, vcc, 0, v197, vcc
	global_load_dwordx4 v[74:77], v[62:63], off offset:3088
	v_add_co_u32_e32 v62, vcc, 0x2000, v194
	s_nop 1
	v_addc_co_u32_e32 v63, vcc, 0, v195, vcc
	global_load_dwordx4 v[62:65], v[62:63], off offset:3088
	s_and_saveexec_b64 s[10:11], s[40:41]
	s_cbranch_execz .LBB0_1069
	v_add_u32_e32 v90, s69, v201
	ds_read_b128 v[94:97], v90 offset:1024
	v_mov_b32_e32 v104, 0
	v_mov_b32_e32 v105, 0
	v_mov_b32_e32 v106, 0
	v_mov_b32_e32 v107, 0
	s_waitcnt lgkmcnt(0)
	v_mov_b32_e32 v93, v97
	v_mov_b32_e32 v92, v96
	v_mov_b32_e32 v91, v95
	v_mov_b32_e32 v90, v94
	s_and_saveexec_b64 s[12:13], s[8:9]
	s_cbranch_execz .LBB0_1068
	v_add_u32_e32 v90, s62, v0
	ds_read_b128 v[90:93], v90 offset:16
	v_mov_b32_e32 v104, v97
	v_mov_b32_e32 v105, v96
	v_mov_b32_e32 v106, v95
	v_mov_b32_e32 v107, v94
